# NSA_QB table: sample slots sum 222, others 286 (sample unit ~64 block-units under load)
# speedup vs baseline: 1.0085x; 1.0067x over previous
_ZL6NSA_QB:
	.byte	111, 64, 47, 0, 110, 65, 46, 1, 109, 66, 45, 2, 108, 67, 44, 3, 107, 68, 43, 4, 106, 69, 42, 5, 105, 70, 41, 6, 104, 71, 40, 7, 103, 72, 39, 8, 102, 73, 38, 9, 101, 74, 37, 10, 100, 75, 36, 11, 99, 76, 35, 12, 98, 77, 34, 13, 97, 78, 33, 14, 96, 79, 32, 15, 127, 80, 63, 16, 126, 81, 62, 17, 125, 82, 61, 18, 124, 83, 60, 19, 123, 84, 59, 20, 122, 85, 58, 21, 121, 86, 57, 22, 120, 87, 56, 23, 119, 88, 55, 24, 118, 89, 54, 25, 117, 90, 53, 26, 116, 91, 52, 27, 115, 92, 51, 28, 114, 93, 50, 29, 113, 94, 49, 30, 112, 95, 48, 31
	.size	_ZL6NSA_QB, 128

	.type	__hip_cuid_aaa9f4bcd633d1df,@object
